# m23 + non-temporal hint on the pooling-mixer MIX stores
# speedup vs baseline: 1.0010x; 1.0010x over previous
; __device__ __forceinline__ float bf_lo(unsigned u) { return __uint_as_float(u << 16); }
; __device__ __forceinline__ float bf_hi(unsigned u) { return __uint_as_float(u & 0xffff0000u); }
; __device__ __forceinline__ void pool_acc(float (&sum)[8], const u32x4 x, float sgn) {
;     sum[0] += sgn * bf_lo(x.x); sum[1] += sgn * bf_hi(x.x); sum[2] += sgn * bf_lo(x.y); sum[3] += sgn * bf_hi(x.y);
;     sum[4] += sgn * bf_lo(x.z); sum[5] += sgn * bf_hi(x.z); sum[6] += sgn * bf_lo(x.w); sum[7] += sgn * bf_hi(x.w); }
; __device__ __forceinline__ void pool_phase(const bf16_t* __restrict__ U3, bf16_t* __restrict__ MIX, unsigned* ctr, int lane) {
;     ...
;         u32x4 wv[16];
; #pragma unroll
;         for (int j = 0; j < 16; ++j) { const int tt = t0 - 8 + j; wv[j] = (j >= 8 - w2 && j < 8 + w2 && tt >= 0 && tt < L) ? *(const u32x4*)XROW(tt) : z4; }
;         float sum[8];
; #pragma unroll
;         for (int e = 0; e < 8; ++e) sum[e] = 0.f;
; #pragma unroll
;         for (int j = 0; j < 16; ++j) pool_acc(sum, wv[j], 1.0f);
.LBB0_550:
	s_or_b64 exec, exec, s[36:37]
	s_waitcnt vmcnt(7)
	v_lshlrev_b32_e32 v179, 16, v4
	v_and_b32_e32 v4, 0xffff0000, v4
	v_add_f32_e32 v4, 0, v4
	v_lshlrev_b32_e32 v180, 16, v5
	v_and_b32_e32 v5, 0xffff0000, v5
	v_lshlrev_b32_e32 v183, 16, v8
	v_and_b32_e32 v8, 0xffff0000, v8
	v_add_f32_e32 v5, 0, v5
	v_lshlrev_b32_e32 v181, 16, v6
	v_and_b32_e32 v6, 0xffff0000, v6
	v_add_f32_e32 v4, v4, v8
	v_lshlrev_b32_e32 v8, 16, v9
	v_and_b32_e32 v9, 0xffff0000, v9
	v_add_f32_e32 v6, 0, v6
	v_lshlrev_b32_e32 v182, 16, v7
	v_and_b32_e32 v7, 0xffff0000, v7
	v_add_f32_e32 v5, v5, v9
	v_lshlrev_b32_e32 v9, 16, v10
	v_and_b32_e32 v10, 0xffff0000, v10
	v_add_f32_e32 v7, 0, v7
	v_add_f32_e32 v6, v6, v10
	v_lshlrev_b32_e32 v10, 16, v11
	v_and_b32_e32 v11, 0xffff0000, v11
	v_add_f32_e32 v180, 0, v180
	v_add_f32_e32 v7, v7, v11
	v_lshlrev_b32_e32 v11, 16, v0
	v_and_b32_e32 v0, 0xffff0000, v0
	v_add_f32_e32 v8, v180, v8
	v_add_f32_e32 v0, v4, v0
	v_lshlrev_b32_e32 v4, 16, v1
	v_add_f32_e32 v4, v8, v4
	v_and_b32_e32 v8, 0xffff0000, v16
	v_add_f32_e32 v181, 0, v181
	v_and_b32_e32 v1, 0xffff0000, v1
	v_add_f32_e32 v0, v0, v8
	v_lshlrev_b32_e32 v8, 16, v17
	v_add_f32_e32 v9, v181, v9
	v_add_f32_e32 v1, v5, v1
	v_lshlrev_b32_e32 v5, 16, v2
	v_add_f32_e32 v4, v4, v8
	v_and_b32_e32 v8, 0xffff0000, v17
	v_add_f32_e32 v182, 0, v182
	v_add_f32_e32 v5, v9, v5
	v_and_b32_e32 v2, 0xffff0000, v2
	v_add_f32_e32 v1, v1, v8
	v_lshlrev_b32_e32 v8, 16, v18
	v_add_f32_e32 v179, 0, v179
	v_add_f32_e32 v10, v182, v10
	v_add_f32_e32 v2, v6, v2
	v_lshlrev_b32_e32 v6, 16, v3
	v_add_f32_e32 v5, v5, v8
	v_and_b32_e32 v8, 0xffff0000, v18
	v_add_f32_e32 v179, v179, v183
	v_add_f32_e32 v6, v10, v6
	v_and_b32_e32 v3, 0xffff0000, v3
	v_add_f32_e32 v2, v2, v8
	v_lshlrev_b32_e32 v8, 16, v19
	v_add_f32_e32 v11, v179, v11
	v_add_f32_e32 v3, v7, v3
	v_lshlrev_b32_e32 v7, 16, v16
	v_add_f32_e32 v6, v6, v8
	v_and_b32_e32 v8, 0xffff0000, v19
	v_add_f32_e32 v7, v11, v7
	v_add_f32_e32 v3, v3, v8
	v_lshlrev_b32_e32 v8, 16, v12
	v_add_f32_e32 v7, v7, v8
	v_and_b32_e32 v8, 0xffff0000, v12
	v_add_f32_e32 v0, v0, v8
	v_lshlrev_b32_e32 v8, 16, v13
	v_add_f32_e32 v4, v4, v8
	v_and_b32_e32 v8, 0xffff0000, v13
	v_add_f32_e32 v1, v1, v8
	v_lshlrev_b32_e32 v8, 16, v14
	v_add_f32_e32 v5, v5, v8
	v_and_b32_e32 v8, 0xffff0000, v14
	v_add_f32_e32 v2, v2, v8
	v_lshlrev_b32_e32 v8, 16, v15
	v_add_f32_e32 v6, v6, v8
	v_and_b32_e32 v8, 0xffff0000, v15
	v_add_f32_e32 v3, v3, v8
	v_lshlrev_b32_e32 v8, 16, v24
	v_add_f32_e32 v7, v7, v8
	v_and_b32_e32 v8, 0xffff0000, v24
	v_add_f32_e32 v0, v0, v8
	v_lshlrev_b32_e32 v8, 16, v25
	v_add_f32_e32 v4, v4, v8
	v_and_b32_e32 v8, 0xffff0000, v25
	v_add_f32_e32 v1, v1, v8
	v_lshlrev_b32_e32 v8, 16, v26
	v_add_f32_e32 v5, v5, v8
	v_and_b32_e32 v8, 0xffff0000, v26
	v_add_f32_e32 v2, v2, v8
	v_lshlrev_b32_e32 v8, 16, v27
	v_add_f32_e32 v6, v6, v8
	v_and_b32_e32 v8, 0xffff0000, v27
	v_add_f32_e32 v3, v3, v8
	v_lshlrev_b32_e32 v8, 16, v20
	v_add_f32_e32 v7, v7, v8
	v_and_b32_e32 v8, 0xffff0000, v20
	v_add_f32_e32 v0, v0, v8
	v_lshlrev_b32_e32 v8, 16, v21
	v_add_f32_e32 v4, v4, v8
	v_and_b32_e32 v8, 0xffff0000, v21
	v_add_f32_e32 v1, v1, v8
	v_lshlrev_b32_e32 v8, 16, v22
	v_add_f32_e32 v5, v5, v8
	v_and_b32_e32 v8, 0xffff0000, v22
	v_add_f32_e32 v2, v2, v8
	v_lshlrev_b32_e32 v8, 16, v23
	v_add_f32_e32 v6, v6, v8
	v_and_b32_e32 v8, 0xffff0000, v23
	v_add_f32_e32 v3, v3, v8
	v_lshlrev_b32_e32 v8, 16, v32
	v_add_f32_e32 v7, v7, v8
	v_and_b32_e32 v8, 0xffff0000, v32
	v_add_f32_e32 v0, v0, v8
	v_lshlrev_b32_e32 v8, 16, v33
	v_add_f32_e32 v4, v4, v8
	v_and_b32_e32 v8, 0xffff0000, v33
	v_add_f32_e32 v1, v1, v8
	v_lshlrev_b32_e32 v8, 16, v34
	v_add_f32_e32 v5, v5, v8
	v_and_b32_e32 v8, 0xffff0000, v34
	v_add_f32_e32 v2, v2, v8
	v_lshlrev_b32_e32 v8, 16, v35
	v_add_f32_e32 v6, v6, v8
	v_and_b32_e32 v8, 0xffff0000, v35
	v_add_f32_e32 v3, v3, v8
	v_lshlrev_b32_e32 v8, 16, v28
	v_add_f32_e32 v7, v7, v8
	v_and_b32_e32 v8, 0xffff0000, v28
	v_add_f32_e32 v0, v0, v8
	v_lshlrev_b32_e32 v8, 16, v29
	v_add_f32_e32 v4, v4, v8
	v_and_b32_e32 v8, 0xffff0000, v29
	v_add_f32_e32 v1, v1, v8
	v_lshlrev_b32_e32 v8, 16, v30
	v_add_f32_e32 v5, v5, v8
	v_and_b32_e32 v8, 0xffff0000, v30
	v_add_f32_e32 v2, v2, v8
	v_lshlrev_b32_e32 v8, 16, v31
	v_add_f32_e32 v6, v6, v8
	v_and_b32_e32 v8, 0xffff0000, v31
	v_add_f32_e32 v3, v3, v8
	v_lshlrev_b32_e32 v8, 16, v48
	v_add_f32_e32 v7, v7, v8
	v_and_b32_e32 v8, 0xffff0000, v48
	v_add_f32_e32 v0, v0, v8
	v_lshlrev_b32_e32 v8, 16, v49
	v_add_f32_e32 v4, v4, v8
	v_and_b32_e32 v8, 0xffff0000, v49
	v_add_f32_e32 v1, v1, v8
	v_lshlrev_b32_e32 v8, 16, v50
	v_add_f32_e32 v5, v5, v8
	v_and_b32_e32 v8, 0xffff0000, v50
	v_add_f32_e32 v2, v2, v8
	v_lshlrev_b32_e32 v8, 16, v51
	v_add_f32_e32 v6, v6, v8
	v_and_b32_e32 v8, 0xffff0000, v51
	v_add_f32_e32 v3, v3, v8
	v_lshlrev_b32_e32 v8, 16, v36
	v_add_f32_e32 v7, v7, v8
	v_and_b32_e32 v8, 0xffff0000, v36
	v_add_f32_e32 v0, v0, v8
	v_lshlrev_b32_e32 v8, 16, v37
	v_add_f32_e32 v4, v4, v8
	v_and_b32_e32 v8, 0xffff0000, v37
	v_add_f32_e32 v1, v1, v8
	v_lshlrev_b32_e32 v8, 16, v38
	v_add_f32_e32 v5, v5, v8
	v_and_b32_e32 v8, 0xffff0000, v38
	v_add_f32_e32 v2, v2, v8
	v_lshlrev_b32_e32 v8, 16, v39
	v_add_f32_e32 v6, v6, v8
	v_and_b32_e32 v8, 0xffff0000, v39
	v_add_f32_e32 v3, v3, v8
	v_lshlrev_b32_e32 v8, 16, v76
	v_add_f32_e32 v7, v7, v8
	v_and_b32_e32 v8, 0xffff0000, v76
	v_add_f32_e32 v0, v0, v8
	v_lshlrev_b32_e32 v8, 16, v77
	v_add_f32_e32 v4, v4, v8
	v_and_b32_e32 v8, 0xffff0000, v77
	v_add_f32_e32 v1, v1, v8
	v_lshlrev_b32_e32 v8, 16, v78
	v_add_f32_e32 v5, v5, v8
	v_and_b32_e32 v8, 0xffff0000, v78
	v_add_f32_e32 v2, v2, v8
; __device__ __forceinline__ unsigned cvt_pk_bf16(float lo, float hi) { unsigned r; asm volatile("v_cvt_pk_bf16_f32 %0, %1, %2" : "=v"(r) : "v"(lo), "v"(hi)); return r; }
; __device__ __forceinline__ float bf_lo(unsigned u) { return __uint_as_float(u << 16); }
; __device__ __forceinline__ float bf_hi(unsigned u) { return __uint_as_float(u & 0xffff0000u); }
; __device__ __forceinline__ void pool_phase(const bf16_t* __restrict__ U3, bf16_t* __restrict__ MIX, unsigned* ctr, int lane) {
;     ...
;         for (int i = 0; i < 8; ++i) { const int t = t0 + i; xc[i] = *(const u32x4*)XROW(t);
;             xa[i] = (t + w2 < L) ? *(const u32x4*)XROW(t + w2) : z4; xs[i] = (t - w2 >= 0) ? *(const u32x4*)XROW(t - w2) : z4; }
; #pragma unroll
;         for (int i = 0; i < 8; ++i) { const int t = t0 + i; const int lo = max(t - w2, 0), hi = min(t + w2, L); const float inv = 1.0f / (float)(hi - lo);
;             const u32x4 x = xc[i];
;             u32x4 o; o.x = cvt_pk_bf16(sum[0] * inv - bf_lo(x.x), sum[1] * inv - bf_hi(x.x)); o.y = cvt_pk_bf16(sum[2] * inv - bf_lo(x.y), sum[3] * inv - bf_hi(x.y));
;             o.z = cvt_pk_bf16(sum[4] * inv - bf_lo(x.z), sum[5] * inv - bf_hi(x.z)); o.w = cvt_pk_bf16(sum[6] * inv - bf_lo(x.w), sum[7] * inv - bf_hi(x.w));
;             *(u32x4*)(MIX + (size_t)(r0 + i) * D + 512 + col) = o;
;             pool_acc(sum, xa[i], 1.0f); pool_acc(sum, xs[i], -1.0f); }
	v_lshlrev_b32_e32 v8, 16, v79
	v_add_f32_e32 v6, v6, v8
	v_and_b32_e32 v8, 0xffff0000, v79
	v_add_f32_e32 v3, v3, v8
	v_lshlrev_b32_e32 v8, 16, v60
	v_add_f32_e32 v7, v7, v8
	v_and_b32_e32 v8, 0xffff0000, v60
	v_add_f32_e32 v0, v0, v8
	v_lshlrev_b32_e32 v8, 16, v61
	v_add_f32_e32 v4, v4, v8
	v_and_b32_e32 v8, 0xffff0000, v61
	v_add_f32_e32 v1, v1, v8
	v_lshlrev_b32_e32 v8, 16, v62
	v_add_f32_e32 v5, v5, v8
	v_and_b32_e32 v8, 0xffff0000, v62
	v_add_f32_e32 v2, v2, v8
	v_lshlrev_b32_e32 v8, 16, v63
	v_add_f32_e32 v6, v6, v8
	v_and_b32_e32 v8, 0xffff0000, v63
	v_add_f32_e32 v3, v3, v8
	v_lshlrev_b32_e32 v8, 16, v120
	v_add_f32_e32 v7, v7, v8
	v_and_b32_e32 v8, 0xffff0000, v120
	v_add_f32_e32 v0, v0, v8
	v_lshlrev_b32_e32 v8, 16, v121
	v_add_f32_e32 v4, v4, v8
	v_and_b32_e32 v8, 0xffff0000, v121
	v_add_f32_e32 v1, v1, v8
	v_lshlrev_b32_e32 v8, 16, v122
	v_add_f32_e32 v5, v5, v8
	v_and_b32_e32 v8, 0xffff0000, v122
	v_add_f32_e32 v2, v2, v8
	v_lshlrev_b32_e32 v8, 16, v123
	v_add_f32_e32 v6, v6, v8
	v_and_b32_e32 v8, 0xffff0000, v123
	v_add_f32_e32 v3, v3, v8
	v_lshlrev_b32_e32 v8, 16, v100
	v_add_f32_e32 v7, v7, v8
	v_and_b32_e32 v8, 0xffff0000, v100
	v_add_f32_e32 v0, v0, v8
	v_lshlrev_b32_e32 v8, 16, v101
	v_add_f32_e32 v4, v4, v8
	v_and_b32_e32 v8, 0xffff0000, v101
	v_add_f32_e32 v1, v1, v8
	v_lshlrev_b32_e32 v8, 16, v102
	v_add_f32_e32 v5, v5, v8
	v_and_b32_e32 v8, 0xffff0000, v102
	v_add_f32_e32 v2, v2, v8
	v_lshlrev_b32_e32 v8, 16, v103
	v_add_f32_e32 v6, v6, v8
	v_and_b32_e32 v8, 0xffff0000, v103
	v_add_f32_e32 v3, v3, v8
	v_lshlrev_b32_e32 v8, 16, v144
	v_add_f32_e32 v12, v7, v8
	v_and_b32_e32 v7, 0xffff0000, v144
	v_add_f32_e32 v13, v0, v7
	v_lshlrev_b32_e32 v0, 16, v145
	v_add_f32_e32 v14, v4, v0
	v_and_b32_e32 v0, 0xffff0000, v145
	v_add_f32_e32 v15, v1, v0
	v_lshlrev_b32_e32 v0, 16, v146
	v_add_f32_e32 v16, v5, v0
	v_and_b32_e32 v0, 0xffff0000, v146
	v_add_f32_e32 v17, v2, v0
	v_lshlrev_b32_e32 v0, 16, v147
	v_add_f32_e32 v18, v6, v0
	v_and_b32_e32 v0, 0xffff0000, v147
	v_add_f32_e32 v19, v3, v0
	v_max_i32_e32 v0, 0, v178
	v_min_i32_e32 v1, s43, v173
	s_cmp_gt_i32 s56, 15
	v_sub_u32_e32 v0, v1, v0
	s_cselect_b32 s36, s62, 0x18000
	v_cvt_f32_i32_e32 v6, v0
	s_sub_i32 s36, s36, s45
	s_add_i32 s36, s84, s36
	s_add_i32 s36, s36, 23
	v_mad_i64_i32 v[0:1], s[36:37], s36, v212, v[148:149]
	v_div_scale_f32 v7, s[36:37], v6, v6, 1.0
	v_rcp_f32_e32 v8, v7
	global_load_dwordx4 v[0:3], v[0:1], off
	s_ashr_i32 s85, s84, 31
	s_lshl_b64 s[36:37], s[84:85], 11
	v_fma_f32 v9, -v7, v8, 1.0
	v_fmac_f32_e32 v8, v9, v8
	v_div_scale_f32 v9, vcc, 1.0, v6, 1.0
	v_mul_f32_e32 v10, v9, v8
	v_fma_f32 v11, -v7, v10, v9
	v_fmac_f32_e32 v10, v11, v8
	v_fma_f32 v7, -v7, v10, v9
	v_div_fmas_f32 v7, v7, v8, v10
	v_div_fixup_f32 v9, v7, v6, 1.0
	s_waitcnt vmcnt(7)
	v_lshlrev_b32_e32 v6, 16, v140
	v_and_b32_e32 v7, 0xffff0000, v140
	v_fma_f32 v6, v9, v12, -v6
	v_fma_f32 v7, v9, v13, -v7
	v_cvt_pk_bf16_f32 v6, v6, v7
	v_lshlrev_b32_e32 v7, 16, v141
	v_and_b32_e32 v8, 0xffff0000, v141
	v_fma_f32 v7, v9, v14, -v7
	v_fma_f32 v8, v9, v15, -v8
	v_cvt_pk_bf16_f32 v7, v7, v8
	v_lshlrev_b32_e32 v8, 16, v142
	v_and_b32_e32 v10, 0xffff0000, v142
	v_fma_f32 v8, v9, v16, -v8
	v_fma_f32 v10, v9, v17, -v10
	v_cvt_pk_bf16_f32 v8, v8, v10
	v_lshlrev_b32_e32 v10, 16, v143
	v_and_b32_e32 v11, 0xffff0000, v143
	v_fma_f32 v10, v9, v18, -v10
	v_fma_f32 v9, v9, v19, -v11
	v_cvt_pk_bf16_f32 v9, v10, v9
	v_lshl_add_u64 v[10:11], v[150:151], 0, s[36:37]
	global_store_dwordx4 v[10:11], v[6:9], off offset:1024 nt
	v_lshlrev_b32_e32 v10, 16, v82
	v_add_f32_e32 v10, v16, v10
	v_lshlrev_b32_e32 v6, 16, v80
	v_lshlrev_b32_e32 v8, 16, v81
	v_add_f32_e32 v6, v12, v6
	v_and_b32_e32 v7, 0xffff0000, v80
	v_add_f32_e32 v8, v14, v8
	v_lshlrev_b32_e32 v14, 16, v136
	v_add_f32_e32 v7, v13, v7
	v_and_b32_e32 v9, 0xffff0000, v81
	v_sub_f32_e32 v14, v6, v14
	v_and_b32_e32 v6, 0xffff0000, v136
	v_add_f32_e32 v9, v15, v9
	v_sub_f32_e32 v15, v7, v6
	v_lshlrev_b32_e32 v6, 16, v137
	v_sub_f32_e32 v16, v8, v6
	v_max_i32_e32 v7, 0, v177
	v_min_i32_e32 v8, s43, v171
	v_sub_u32_e32 v7, v8, v7
	v_cvt_f32_i32_e32 v7, v7
	v_and_b32_e32 v11, 0xffff0000, v82
	v_and_b32_e32 v6, 0xffff0000, v137
	v_add_f32_e32 v11, v17, v11
	v_div_scale_f32 v8, s[36:37], v7, v7, 1.0
	v_lshlrev_b32_e32 v12, 16, v83
	v_sub_f32_e32 v17, v9, v6
	v_lshlrev_b32_e32 v6, 16, v138
	v_rcp_f32_e32 v9, v8
	v_add_f32_e32 v12, v18, v12
	v_and_b32_e32 v13, 0xffff0000, v83
	v_sub_f32_e32 v18, v10, v6
	v_and_b32_e32 v6, 0xffff0000, v138
	v_add_f32_e32 v13, v19, v13
	v_sub_f32_e32 v19, v11, v6
	v_lshlrev_b32_e32 v6, 16, v139
	v_sub_f32_e32 v12, v12, v6
	v_and_b32_e32 v6, 0xffff0000, v139
	v_sub_f32_e32 v13, v13, v6
	v_fma_f32 v6, -v8, v9, 1.0
	v_fmac_f32_e32 v9, v6, v9
	v_div_scale_f32 v6, vcc, 1.0, v7, 1.0
	v_mul_f32_e32 v10, v6, v9
	v_fma_f32 v11, -v8, v10, v6
	v_fmac_f32_e32 v10, v11, v9
	v_fma_f32 v6, -v8, v10, v6
	v_div_fmas_f32 v6, v6, v9, v10
	v_div_fixup_f32 v9, v6, v7, 1.0
	s_waitcnt vmcnt(7)
; __device__ __forceinline__ unsigned cvt_pk_bf16(float lo, float hi) { unsigned r; asm volatile("v_cvt_pk_bf16_f32 %0, %1, %2" : "=v"(r) : "v"(lo), "v"(hi)); return r; }
; __device__ __forceinline__ float bf_lo(unsigned u) { return __uint_as_float(u << 16); }
; __device__ __forceinline__ float bf_hi(unsigned u) { return __uint_as_float(u & 0xffff0000u); }
; __device__ __forceinline__ void pool_phase(const bf16_t* __restrict__ U3, bf16_t* __restrict__ MIX, unsigned* ctr, int lane) {
;     ...
;         for (int i = 0; i < 8; ++i) { const int t = t0 + i; const int lo = max(t - w2, 0), hi = min(t + w2, L); const float inv = 1.0f / (float)(hi - lo);
;             const u32x4 x = xc[i];
;             u32x4 o; o.x = cvt_pk_bf16(sum[0] * inv - bf_lo(x.x), sum[1] * inv - bf_hi(x.x)); o.y = cvt_pk_bf16(sum[2] * inv - bf_lo(x.y), sum[3] * inv - bf_hi(x.y));
;             o.z = cvt_pk_bf16(sum[4] * inv - bf_lo(x.z), sum[5] * inv - bf_hi(x.z)); o.w = cvt_pk_bf16(sum[6] * inv - bf_lo(x.w), sum[7] * inv - bf_hi(x.w));
;             *(u32x4*)(MIX + (size_t)(r0 + i) * D + 512 + col) = o;
;             pool_acc(sum, xa[i], 1.0f); pool_acc(sum, xs[i], -1.0f); }
	v_lshlrev_b32_e32 v6, 16, v132
	v_and_b32_e32 v7, 0xffff0000, v132
	v_fma_f32 v6, v9, v14, -v6
	v_fma_f32 v7, v9, v15, -v7
	v_cvt_pk_bf16_f32 v6, v6, v7
	v_lshlrev_b32_e32 v7, 16, v133
	v_and_b32_e32 v8, 0xffff0000, v133
	v_fma_f32 v7, v9, v16, -v7
	v_fma_f32 v8, v9, v17, -v8
	v_cvt_pk_bf16_f32 v7, v7, v8
	v_lshlrev_b32_e32 v8, 16, v134
	v_and_b32_e32 v10, 0xffff0000, v134
	v_fma_f32 v8, v9, v18, -v8
	v_fma_f32 v10, v9, v19, -v10
	s_add_i32 s36, s84, 1
	v_cvt_pk_bf16_f32 v8, v8, v10
	v_lshlrev_b32_e32 v10, 16, v135
	v_and_b32_e32 v11, 0xffff0000, v135
	s_ashr_i32 s37, s36, 31
	v_fma_f32 v10, v9, v12, -v10
	v_fma_f32 v9, v9, v13, -v11
	s_lshl_b64 s[36:37], s[36:37], 11
	v_cvt_pk_bf16_f32 v9, v10, v9
	v_lshl_add_u64 v[10:11], v[150:151], 0, s[36:37]
	global_store_dwordx4 v[10:11], v[6:9], off offset:1024 nt
	v_lshlrev_b32_e32 v10, 16, v74
	v_add_f32_e32 v10, v18, v10
	v_lshlrev_b32_e32 v6, 16, v72
	v_add_f32_e32 v6, v14, v6
	v_lshlrev_b32_e32 v14, 16, v75
	v_add_f32_e32 v12, v12, v14
	v_and_b32_e32 v14, 0xffff0000, v75
	v_and_b32_e32 v7, 0xffff0000, v72
	v_add_f32_e32 v13, v13, v14
	v_lshlrev_b32_e32 v14, 16, v128
	v_add_f32_e32 v7, v15, v7
	v_lshlrev_b32_e32 v8, 16, v73
	v_sub_f32_e32 v14, v6, v14
	v_and_b32_e32 v6, 0xffff0000, v128
	v_add_f32_e32 v8, v16, v8
	v_sub_f32_e32 v15, v7, v6
	v_lshlrev_b32_e32 v6, 16, v129
	v_sub_f32_e32 v16, v8, v6
	v_max_i32_e32 v7, 0, v175
	v_min_i32_e32 v8, s43, v168
	v_sub_u32_e32 v7, v8, v7
	v_cvt_f32_i32_e32 v7, v7
	v_and_b32_e32 v9, 0xffff0000, v73
	v_add_f32_e32 v9, v17, v9
	v_and_b32_e32 v6, 0xffff0000, v129
	v_div_scale_f32 v8, s[36:37], v7, v7, 1.0
	v_and_b32_e32 v11, 0xffff0000, v74
	v_sub_f32_e32 v17, v9, v6
	v_lshlrev_b32_e32 v6, 16, v130
	v_rcp_f32_e32 v9, v8
	v_add_f32_e32 v11, v19, v11
	v_sub_f32_e32 v18, v10, v6
	v_and_b32_e32 v6, 0xffff0000, v130
	v_sub_f32_e32 v19, v11, v6
	v_lshlrev_b32_e32 v6, 16, v131
	v_sub_f32_e32 v12, v12, v6
	v_and_b32_e32 v6, 0xffff0000, v131
	v_sub_f32_e32 v13, v13, v6
	v_fma_f32 v6, -v8, v9, 1.0
	v_fmac_f32_e32 v9, v6, v9
	v_div_scale_f32 v6, vcc, 1.0, v7, 1.0
	v_mul_f32_e32 v10, v6, v9
	v_fma_f32 v11, -v8, v10, v6
	v_fmac_f32_e32 v10, v11, v9
	v_fma_f32 v6, -v8, v10, v6
	v_div_fmas_f32 v6, v6, v9, v10
	v_div_fixup_f32 v9, v6, v7, 1.0
	s_waitcnt vmcnt(7)
	v_lshlrev_b32_e32 v6, 16, v124
	v_and_b32_e32 v7, 0xffff0000, v124
	v_fma_f32 v6, v9, v14, -v6
	v_fma_f32 v7, v9, v15, -v7
	v_cvt_pk_bf16_f32 v6, v6, v7
	v_lshlrev_b32_e32 v7, 16, v125
	v_and_b32_e32 v8, 0xffff0000, v125
	v_fma_f32 v7, v9, v16, -v7
	v_fma_f32 v8, v9, v17, -v8
	v_cvt_pk_bf16_f32 v7, v7, v8
	v_lshlrev_b32_e32 v8, 16, v126
	v_and_b32_e32 v10, 0xffff0000, v126
	v_fma_f32 v8, v9, v18, -v8
	v_fma_f32 v10, v9, v19, -v10
	s_add_i32 s36, s84, 2
	v_cvt_pk_bf16_f32 v8, v8, v10
	v_lshlrev_b32_e32 v10, 16, v127
	v_and_b32_e32 v11, 0xffff0000, v127
	s_ashr_i32 s37, s36, 31
	v_fma_f32 v10, v9, v12, -v10
	v_fma_f32 v9, v9, v13, -v11
	s_lshl_b64 s[36:37], s[36:37], 11
	v_cvt_pk_bf16_f32 v9, v10, v9
	v_lshl_add_u64 v[10:11], v[150:151], 0, s[36:37]
	global_store_dwordx4 v[10:11], v[6:9], off offset:1024 nt
	v_lshlrev_b32_e32 v10, 16, v66
	v_add_f32_e32 v10, v18, v10
	v_lshlrev_b32_e32 v6, 16, v64
	v_add_f32_e32 v6, v14, v6
	v_lshlrev_b32_e32 v14, 16, v67
	v_add_f32_e32 v12, v12, v14
	v_and_b32_e32 v14, 0xffff0000, v67
	v_and_b32_e32 v7, 0xffff0000, v64
	v_add_f32_e32 v13, v13, v14
	v_lshlrev_b32_e32 v14, 16, v116
	v_add_f32_e32 v7, v15, v7
	v_lshlrev_b32_e32 v8, 16, v65
	v_sub_f32_e32 v14, v6, v14
	v_and_b32_e32 v6, 0xffff0000, v116
	v_add_f32_e32 v8, v16, v8
	v_sub_f32_e32 v15, v7, v6
	v_lshlrev_b32_e32 v6, 16, v117
	v_sub_f32_e32 v16, v8, v6
	v_max_i32_e32 v7, 0, v174
	v_min_i32_e32 v8, s43, v159
	v_sub_u32_e32 v7, v8, v7
	v_cvt_f32_i32_e32 v7, v7
	v_and_b32_e32 v9, 0xffff0000, v65
	v_add_f32_e32 v9, v17, v9
	v_and_b32_e32 v6, 0xffff0000, v117
	v_div_scale_f32 v8, s[36:37], v7, v7, 1.0
	v_and_b32_e32 v11, 0xffff0000, v66
	v_sub_f32_e32 v17, v9, v6
	v_lshlrev_b32_e32 v6, 16, v118
	v_rcp_f32_e32 v9, v8
	v_add_f32_e32 v11, v19, v11
	v_sub_f32_e32 v18, v10, v6
	v_and_b32_e32 v6, 0xffff0000, v118
	v_sub_f32_e32 v19, v11, v6
	v_lshlrev_b32_e32 v6, 16, v119
	v_sub_f32_e32 v12, v12, v6
	v_and_b32_e32 v6, 0xffff0000, v119
	v_sub_f32_e32 v13, v13, v6
	v_fma_f32 v6, -v8, v9, 1.0
	v_fmac_f32_e32 v9, v6, v9
	v_div_scale_f32 v6, vcc, 1.0, v7, 1.0
	v_mul_f32_e32 v10, v6, v9
	v_fma_f32 v11, -v8, v10, v6
	v_fmac_f32_e32 v10, v11, v9
	v_fma_f32 v6, -v8, v10, v6
	v_div_fmas_f32 v6, v6, v9, v10
	v_div_fixup_f32 v9, v6, v7, 1.0
	s_waitcnt vmcnt(7)
; __device__ __forceinline__ unsigned cvt_pk_bf16(float lo, float hi) { unsigned r; asm volatile("v_cvt_pk_bf16_f32 %0, %1, %2" : "=v"(r) : "v"(lo), "v"(hi)); return r; }
; __device__ __forceinline__ float bf_lo(unsigned u) { return __uint_as_float(u << 16); }
; __device__ __forceinline__ float bf_hi(unsigned u) { return __uint_as_float(u & 0xffff0000u); }
; __device__ __forceinline__ void pool_phase(const bf16_t* __restrict__ U3, bf16_t* __restrict__ MIX, unsigned* ctr, int lane) {
;     ...
;         for (int i = 0; i < 8; ++i) { const int t = t0 + i; const int lo = max(t - w2, 0), hi = min(t + w2, L); const float inv = 1.0f / (float)(hi - lo);
;             const u32x4 x = xc[i];
;             u32x4 o; o.x = cvt_pk_bf16(sum[0] * inv - bf_lo(x.x), sum[1] * inv - bf_hi(x.x)); o.y = cvt_pk_bf16(sum[2] * inv - bf_lo(x.y), sum[3] * inv - bf_hi(x.y));
;             o.z = cvt_pk_bf16(sum[4] * inv - bf_lo(x.z), sum[5] * inv - bf_hi(x.z)); o.w = cvt_pk_bf16(sum[6] * inv - bf_lo(x.w), sum[7] * inv - bf_hi(x.w));
;             *(u32x4*)(MIX + (size_t)(r0 + i) * D + 512 + col) = o;
;             pool_acc(sum, xa[i], 1.0f); pool_acc(sum, xs[i], -1.0f); }
	v_lshlrev_b32_e32 v6, 16, v112
	v_and_b32_e32 v7, 0xffff0000, v112
	v_fma_f32 v6, v9, v14, -v6
	v_fma_f32 v7, v9, v15, -v7
	v_cvt_pk_bf16_f32 v6, v6, v7
	v_lshlrev_b32_e32 v7, 16, v113
	v_and_b32_e32 v8, 0xffff0000, v113
	v_fma_f32 v7, v9, v16, -v7
	v_fma_f32 v8, v9, v17, -v8
	v_cvt_pk_bf16_f32 v7, v7, v8
	v_lshlrev_b32_e32 v8, 16, v114
	v_and_b32_e32 v10, 0xffff0000, v114
	v_fma_f32 v8, v9, v18, -v8
	v_fma_f32 v10, v9, v19, -v10
	s_add_i32 s36, s84, 3
	v_cvt_pk_bf16_f32 v8, v8, v10
	v_lshlrev_b32_e32 v10, 16, v115
	v_and_b32_e32 v11, 0xffff0000, v115
	s_ashr_i32 s37, s36, 31
	v_fma_f32 v10, v9, v12, -v10
	v_fma_f32 v9, v9, v13, -v11
	s_lshl_b64 s[36:37], s[36:37], 11
	v_cvt_pk_bf16_f32 v9, v10, v9
	v_lshl_add_u64 v[10:11], v[150:151], 0, s[36:37]
	global_store_dwordx4 v[10:11], v[6:9], off offset:1024 nt
	v_lshlrev_b32_e32 v10, 16, v58
	v_add_f32_e32 v10, v18, v10
	v_lshlrev_b32_e32 v6, 16, v56
	v_add_f32_e32 v6, v14, v6
	v_lshlrev_b32_e32 v14, 16, v59
	v_add_f32_e32 v12, v12, v14
	v_and_b32_e32 v14, 0xffff0000, v59
	v_and_b32_e32 v7, 0xffff0000, v56
	v_add_f32_e32 v13, v13, v14
	v_lshlrev_b32_e32 v14, 16, v108
	v_add_f32_e32 v7, v15, v7
	v_lshlrev_b32_e32 v8, 16, v57
	v_sub_f32_e32 v14, v6, v14
	v_and_b32_e32 v6, 0xffff0000, v108
	v_add_f32_e32 v8, v16, v8
	v_sub_f32_e32 v15, v7, v6
	v_lshlrev_b32_e32 v6, 16, v109
	v_sub_f32_e32 v16, v8, v6
	v_max_i32_e32 v7, 0, v172
	v_min_i32_e32 v8, s43, v158
	v_sub_u32_e32 v7, v8, v7
	v_cvt_f32_i32_e32 v7, v7
	v_and_b32_e32 v9, 0xffff0000, v57
	v_add_f32_e32 v9, v17, v9
	v_and_b32_e32 v6, 0xffff0000, v109
	v_div_scale_f32 v8, s[36:37], v7, v7, 1.0
	v_and_b32_e32 v11, 0xffff0000, v58
	v_sub_f32_e32 v17, v9, v6
	v_lshlrev_b32_e32 v6, 16, v110
	v_rcp_f32_e32 v9, v8
	v_add_f32_e32 v11, v19, v11
	v_sub_f32_e32 v18, v10, v6
	v_and_b32_e32 v6, 0xffff0000, v110
	v_sub_f32_e32 v19, v11, v6
	v_lshlrev_b32_e32 v6, 16, v111
	v_sub_f32_e32 v12, v12, v6
	v_and_b32_e32 v6, 0xffff0000, v111
	v_sub_f32_e32 v13, v13, v6
	v_fma_f32 v6, -v8, v9, 1.0
	v_fmac_f32_e32 v9, v6, v9
	v_div_scale_f32 v6, vcc, 1.0, v7, 1.0
	v_mul_f32_e32 v10, v6, v9
	v_fma_f32 v11, -v8, v10, v6
	v_fmac_f32_e32 v10, v11, v9
	v_fma_f32 v6, -v8, v10, v6
	v_div_fmas_f32 v6, v6, v9, v10
	v_div_fixup_f32 v9, v6, v7, 1.0
	s_waitcnt vmcnt(7)
	v_lshlrev_b32_e32 v6, 16, v104
	v_and_b32_e32 v7, 0xffff0000, v104
	v_fma_f32 v6, v9, v14, -v6
	v_fma_f32 v7, v9, v15, -v7
	v_cvt_pk_bf16_f32 v6, v6, v7
	v_lshlrev_b32_e32 v7, 16, v105
	v_and_b32_e32 v8, 0xffff0000, v105
	v_fma_f32 v7, v9, v16, -v7
	v_fma_f32 v8, v9, v17, -v8
	v_cvt_pk_bf16_f32 v7, v7, v8
	v_lshlrev_b32_e32 v8, 16, v106
	v_and_b32_e32 v10, 0xffff0000, v106
	v_fma_f32 v8, v9, v18, -v8
	v_fma_f32 v10, v9, v19, -v10
	s_add_i32 s36, s84, 4
	v_cvt_pk_bf16_f32 v8, v8, v10
	v_lshlrev_b32_e32 v10, 16, v107
	v_and_b32_e32 v11, 0xffff0000, v107
	s_ashr_i32 s37, s36, 31
	v_fma_f32 v10, v9, v12, -v10
	v_fma_f32 v9, v9, v13, -v11
	s_lshl_b64 s[36:37], s[36:37], 11
	v_cvt_pk_bf16_f32 v9, v10, v9
	v_lshl_add_u64 v[10:11], v[150:151], 0, s[36:37]
	global_store_dwordx4 v[10:11], v[6:9], off offset:1024 nt
	v_lshlrev_b32_e32 v10, 16, v54
	v_add_f32_e32 v10, v18, v10
	v_lshlrev_b32_e32 v6, 16, v52
	v_add_f32_e32 v6, v14, v6
	v_lshlrev_b32_e32 v14, 16, v55
	v_add_f32_e32 v12, v12, v14
	v_and_b32_e32 v14, 0xffff0000, v55
	v_and_b32_e32 v7, 0xffff0000, v52
	v_add_f32_e32 v13, v13, v14
	v_lshlrev_b32_e32 v14, 16, v96
	v_add_f32_e32 v7, v15, v7
	v_lshlrev_b32_e32 v8, 16, v53
	v_sub_f32_e32 v14, v6, v14
	v_and_b32_e32 v6, 0xffff0000, v96
	v_add_f32_e32 v8, v16, v8
	v_sub_f32_e32 v15, v7, v6
	v_lshlrev_b32_e32 v6, 16, v97
	v_sub_f32_e32 v16, v8, v6
	v_max_i32_e32 v7, 0, v169
	v_min_i32_e32 v8, s43, v157
	v_sub_u32_e32 v7, v8, v7
	v_cvt_f32_i32_e32 v7, v7
	v_and_b32_e32 v9, 0xffff0000, v53
	v_add_f32_e32 v9, v17, v9
	v_and_b32_e32 v6, 0xffff0000, v97
	v_div_scale_f32 v8, s[36:37], v7, v7, 1.0
	v_and_b32_e32 v11, 0xffff0000, v54
	v_sub_f32_e32 v17, v9, v6
	v_lshlrev_b32_e32 v6, 16, v98
	v_rcp_f32_e32 v9, v8
	v_add_f32_e32 v11, v19, v11
	v_sub_f32_e32 v18, v10, v6
	v_and_b32_e32 v6, 0xffff0000, v98
	v_sub_f32_e32 v19, v11, v6
	v_lshlrev_b32_e32 v6, 16, v99
	v_sub_f32_e32 v12, v12, v6
	v_and_b32_e32 v6, 0xffff0000, v99
	v_sub_f32_e32 v13, v13, v6
	v_fma_f32 v6, -v8, v9, 1.0
	v_fmac_f32_e32 v9, v6, v9
	v_div_scale_f32 v6, vcc, 1.0, v7, 1.0
	v_mul_f32_e32 v10, v6, v9
	v_fma_f32 v11, -v8, v10, v6
	v_fmac_f32_e32 v10, v11, v9
	v_fma_f32 v6, -v8, v10, v6
	v_div_fmas_f32 v6, v6, v9, v10
	v_div_fixup_f32 v9, v6, v7, 1.0
	s_waitcnt vmcnt(7)
; __device__ __forceinline__ unsigned cvt_pk_bf16(float lo, float hi) { unsigned r; asm volatile("v_cvt_pk_bf16_f32 %0, %1, %2" : "=v"(r) : "v"(lo), "v"(hi)); return r; }
; __device__ __forceinline__ float bf_lo(unsigned u) { return __uint_as_float(u << 16); }
; __device__ __forceinline__ float bf_hi(unsigned u) { return __uint_as_float(u & 0xffff0000u); }
; __device__ __forceinline__ void pool_phase(const bf16_t* __restrict__ U3, bf16_t* __restrict__ MIX, unsigned* ctr, int lane) {
;     ...
;     for (int task = base; task < base + 4; ++task) {
;     ...
;         for (int i = 0; i < 8; ++i) { const int t = t0 + i; const int lo = max(t - w2, 0), hi = min(t + w2, L); const float inv = 1.0f / (float)(hi - lo);
;             const u32x4 x = xc[i];
;             u32x4 o; o.x = cvt_pk_bf16(sum[0] * inv - bf_lo(x.x), sum[1] * inv - bf_hi(x.x)); o.y = cvt_pk_bf16(sum[2] * inv - bf_lo(x.y), sum[3] * inv - bf_hi(x.y));
;             o.z = cvt_pk_bf16(sum[4] * inv - bf_lo(x.z), sum[5] * inv - bf_hi(x.z)); o.w = cvt_pk_bf16(sum[6] * inv - bf_lo(x.w), sum[7] * inv - bf_hi(x.w));
;             *(u32x4*)(MIX + (size_t)(r0 + i) * D + 512 + col) = o;
;             pool_acc(sum, xa[i], 1.0f); pool_acc(sum, xs[i], -1.0f); }
;     }
	v_lshlrev_b32_e32 v6, 16, v92
	v_and_b32_e32 v7, 0xffff0000, v92
	v_fma_f32 v6, v9, v14, -v6
	v_fma_f32 v7, v9, v15, -v7
	v_cvt_pk_bf16_f32 v6, v6, v7
	v_lshlrev_b32_e32 v7, 16, v93
	v_and_b32_e32 v8, 0xffff0000, v93
	v_fma_f32 v7, v9, v16, -v7
	v_fma_f32 v8, v9, v17, -v8
	v_cvt_pk_bf16_f32 v7, v7, v8
	v_lshlrev_b32_e32 v8, 16, v94
	v_and_b32_e32 v10, 0xffff0000, v94
	v_fma_f32 v8, v9, v18, -v8
	v_fma_f32 v10, v9, v19, -v10
	s_add_i32 s36, s84, 5
	v_cvt_pk_bf16_f32 v8, v8, v10
	v_lshlrev_b32_e32 v10, 16, v95
	v_and_b32_e32 v11, 0xffff0000, v95
	s_ashr_i32 s37, s36, 31
	v_fma_f32 v10, v9, v12, -v10
	v_fma_f32 v9, v9, v13, -v11
	s_lshl_b64 s[36:37], s[36:37], 11
	v_cvt_pk_bf16_f32 v9, v10, v9
	v_lshl_add_u64 v[10:11], v[150:151], 0, s[36:37]
	global_store_dwordx4 v[10:11], v[6:9], off offset:1024 nt
	v_lshlrev_b32_e32 v10, 16, v46
	v_add_f32_e32 v10, v18, v10
	v_lshlrev_b32_e32 v6, 16, v44
	v_add_f32_e32 v6, v14, v6
	v_lshlrev_b32_e32 v14, 16, v47
	v_add_f32_e32 v12, v12, v14
	v_and_b32_e32 v14, 0xffff0000, v47
	v_and_b32_e32 v7, 0xffff0000, v44
	v_add_f32_e32 v13, v13, v14
	v_lshlrev_b32_e32 v14, 16, v88
	v_add_f32_e32 v7, v15, v7
	v_lshlrev_b32_e32 v8, 16, v45
	v_sub_f32_e32 v14, v6, v14
	v_and_b32_e32 v6, 0xffff0000, v88
	v_add_f32_e32 v8, v16, v8
	v_sub_f32_e32 v15, v7, v6
	v_lshlrev_b32_e32 v6, 16, v89
	v_sub_f32_e32 v16, v8, v6
	v_max_i32_e32 v7, 0, v160
	v_min_i32_e32 v8, s43, v156
	v_sub_u32_e32 v7, v8, v7
	v_cvt_f32_i32_e32 v7, v7
	v_and_b32_e32 v9, 0xffff0000, v45
	v_add_f32_e32 v9, v17, v9
	v_and_b32_e32 v6, 0xffff0000, v89
	v_div_scale_f32 v8, s[36:37], v7, v7, 1.0
	v_and_b32_e32 v11, 0xffff0000, v46
	v_sub_f32_e32 v17, v9, v6
	v_lshlrev_b32_e32 v6, 16, v90
	v_rcp_f32_e32 v9, v8
	v_add_f32_e32 v11, v19, v11
	v_sub_f32_e32 v18, v10, v6
	v_and_b32_e32 v6, 0xffff0000, v90
	v_sub_f32_e32 v19, v11, v6
	v_lshlrev_b32_e32 v6, 16, v91
	v_sub_f32_e32 v12, v12, v6
	v_and_b32_e32 v6, 0xffff0000, v91
	v_sub_f32_e32 v13, v13, v6
	v_fma_f32 v6, -v8, v9, 1.0
	v_fmac_f32_e32 v9, v6, v9
	v_div_scale_f32 v6, vcc, 1.0, v7, 1.0
	v_mul_f32_e32 v10, v6, v9
	v_fma_f32 v11, -v8, v10, v6
	v_fmac_f32_e32 v10, v11, v9
	v_fma_f32 v6, -v8, v10, v6
	v_div_fmas_f32 v6, v6, v9, v10
	v_div_fixup_f32 v9, v6, v7, 1.0
	s_waitcnt vmcnt(7)
	v_lshlrev_b32_e32 v6, 16, v84
	v_and_b32_e32 v7, 0xffff0000, v84
	v_fma_f32 v6, v9, v14, -v6
	v_fma_f32 v7, v9, v15, -v7
	v_cvt_pk_bf16_f32 v6, v6, v7
	v_lshlrev_b32_e32 v7, 16, v85
	v_and_b32_e32 v8, 0xffff0000, v85
	v_fma_f32 v7, v9, v16, -v7
	v_fma_f32 v8, v9, v17, -v8
	v_cvt_pk_bf16_f32 v7, v7, v8
	v_lshlrev_b32_e32 v8, 16, v86
	v_and_b32_e32 v10, 0xffff0000, v86
	v_fma_f32 v8, v9, v18, -v8
	v_fma_f32 v10, v9, v19, -v10
	s_add_i32 s36, s84, 6
	v_cvt_pk_bf16_f32 v8, v8, v10
	v_lshlrev_b32_e32 v10, 16, v87
	v_and_b32_e32 v11, 0xffff0000, v87
	s_ashr_i32 s37, s36, 31
	v_fma_f32 v10, v9, v12, -v10
	v_fma_f32 v9, v9, v13, -v11
	s_lshl_b64 s[36:37], s[36:37], 11
	v_cvt_pk_bf16_f32 v9, v10, v9
	v_lshl_add_u64 v[10:11], v[150:151], 0, s[36:37]
	global_store_dwordx4 v[10:11], v[6:9], off offset:1024 nt
	v_add_u32_e32 v4, 23, v170
	v_add_u32_e32 v5, 23, v176
	v_lshlrev_b32_e32 v6, 16, v40
	v_add_f32_e32 v6, v14, v6
	v_lshlrev_b32_e32 v14, 16, v43
	v_add_f32_e32 v12, v12, v14
	v_and_b32_e32 v14, 0xffff0000, v43
	v_and_b32_e32 v7, 0xffff0000, v40
	v_add_f32_e32 v13, v13, v14
	v_lshlrev_b32_e32 v14, 16, v68
	v_max_i32_e32 v5, 0, v5
	v_min_i32_e32 v4, s43, v4
	v_add_f32_e32 v7, v15, v7
	v_lshlrev_b32_e32 v8, 16, v41
	v_sub_f32_e32 v6, v6, v14
	v_and_b32_e32 v14, 0xffff0000, v68
	v_sub_u32_e32 v4, v4, v5
	v_add_f32_e32 v8, v16, v8
	v_and_b32_e32 v9, 0xffff0000, v41
	v_sub_f32_e32 v7, v7, v14
	v_lshlrev_b32_e32 v14, 16, v69
	v_cvt_f32_i32_e32 v4, v4
	v_add_f32_e32 v9, v17, v9
	v_lshlrev_b32_e32 v10, 16, v42
	v_sub_f32_e32 v8, v8, v14
	v_and_b32_e32 v14, 0xffff0000, v69
	v_add_f32_e32 v10, v18, v10
	v_and_b32_e32 v11, 0xffff0000, v42
	v_sub_f32_e32 v9, v9, v14
	v_lshlrev_b32_e32 v14, 16, v70
	v_add_f32_e32 v11, v19, v11
	v_sub_f32_e32 v10, v10, v14
	v_and_b32_e32 v14, 0xffff0000, v70
	v_sub_f32_e32 v5, v11, v14
	v_div_scale_f32 v14, s[36:37], v4, v4, 1.0
	v_rcp_f32_e32 v15, v14
	v_lshlrev_b32_e32 v11, 16, v71
	v_sub_f32_e32 v11, v12, v11
	v_and_b32_e32 v12, 0xffff0000, v71
	v_sub_f32_e32 v12, v13, v12
	v_fma_f32 v13, -v14, v15, 1.0
	v_fmac_f32_e32 v15, v13, v15
	v_div_scale_f32 v13, vcc, 1.0, v4, 1.0
	v_mul_f32_e32 v16, v13, v15
	v_fma_f32 v17, -v14, v16, v13
	v_fmac_f32_e32 v16, v17, v15
	v_fma_f32 v13, -v14, v16, v13
	v_div_fmas_f32 v13, v13, v15, v16
	v_div_fixup_f32 v4, v13, v4, 1.0
	s_waitcnt vmcnt(7)
	v_lshlrev_b32_e32 v13, 16, v0
	v_and_b32_e32 v0, 0xffff0000, v0
	v_fma_f32 v6, v4, v6, -v13
	v_fma_f32 v0, v4, v7, -v0
	v_cvt_pk_bf16_f32 v0, v6, v0
	v_lshlrev_b32_e32 v6, 16, v1
	v_and_b32_e32 v1, 0xffff0000, v1
	v_fma_f32 v6, v4, v8, -v6
	v_fma_f32 v1, v4, v9, -v1
	v_cvt_pk_bf16_f32 v1, v6, v1
	v_lshlrev_b32_e32 v6, 16, v2
	v_and_b32_e32 v2, 0xffff0000, v2
	s_add_i32 s36, s84, 7
	v_fma_f32 v2, v4, v5, -v2
	v_lshlrev_b32_e32 v5, 16, v3
	v_and_b32_e32 v3, 0xffff0000, v3
	s_ashr_i32 s37, s36, 31
	v_fma_f32 v5, v4, v11, -v5
	v_fma_f32 v3, v4, v12, -v3
	s_lshl_b64 s[36:37], s[36:37], 11
	s_add_i32 s4, s4, 1
	s_add_i32 s33, s33, 8
	v_fma_f32 v6, v4, v10, -v6
	v_cvt_pk_bf16_f32 v2, v6, v2
	v_cvt_pk_bf16_f32 v3, v5, v3
	v_lshl_add_u64 v[4:5], v[150:151], 0, s[36:37]
	s_cmp_eq_u32 s33, 32
	global_store_dwordx4 v[4:5], v[0:3], off offset:1024 nt
	s_cbranch_scc1 .LBB0_542
